# tile-loop header: 64-bit VALU compares and mask round trip replaced by scalar compare and select
# speedup vs baseline: 1.0087x; 1.0042x over previous
.LBB0_515:
	s_add_i32 s36, s36, 1
	s_mul_i32 s8, s36, s46
	s_mul_hi_u32 s9, s36, s77
	s_add_i32 s9, s9, s8
	s_mul_i32 s8, s36, s77
	s_mov_b64 s[84:85], s[12:13]
	s_add_u32 s12, s8, s34
	s_addc_u32 s13, s9, s73
	s_cmp_ge_u32 s12, s42
	s_cselect_b64 s[8:9], -1, 0
	s_mov_b64 s[78:79], s[48:49]
	s_mov_b32 s20, s69
	s_mov_b32 s25, s80
	s_not_b64 s[10:11], s[8:9]
	s_and_b64 vcc, exec, s[8:9]
	s_cbranch_vccnz .LBB0_517
	s_lshr_b32 s12, s77, 6
	s_add_i32 s80, s80, s12
	s_lshr_b32 s13, s37, 3
	s_cmp_ge_i32 s80, s13
	s_cbranch_scc0 .Lti_done
	s_sub_i32 s80, s80, s13
	s_add_i32 s69, s69, 8
	s_cmp_ge_i32 s80, s13
	s_cbranch_scc0 .Lti_done
	s_sub_i32 s80, s80, s13
	s_add_i32 s69, s69, 8
.Lti_done:
.LBB0_517:
	s_mov_b64 s[12:13], s[8:9]
	s_andn2_b64 vcc, exec, s[10:11]
	s_mov_b64 s[48:49], s[78:79]
	s_cbranch_vccnz .LBB0_519
	s_ashr_i32 s10, s69, 31
	s_mul_hi_u32 s11, s30, s69
	s_mul_i32 s10, s30, s10
	s_add_i32 s10, s11, s10
	s_mul_i32 s11, s31, s69
	s_add_i32 s10, s10, s11
	s_mul_i32 s11, s30, s69
	s_add_u32 s48, s92, s11
	s_addc_u32 s49, s93, s10
